# conv item staging loads (16 AG rows) and attention mode-1 OB read-back loads (8 per half) each issued as one batch with a single wait; stacked on v006
# baseline (speedup 1.0000x reference)
; __device__ __forceinline__ int crow(int r, int hi) { return (r & 3) + 8 * (r >> 2) + 4 * hi; }
; __device__ __forceinline__ void attn_pass(const bf16_t* __restrict__ Qb, const bf16_t* __restrict__ Kh, const bf16_t* __restrict__ Vh,
;                                           float* Ob, int mode, float lam, int qpos0, int seq, char* lds, const int wv, bf16_t* OBh) {
;     ...
;   if (hi == 0) li_l[r32] = l_reg; asm volatile("s_waitcnt lgkmcnt(0)" ::: "memory");
;   float rli[16];
; #pragma unroll
;   for (int r = 0; r < 16; ++r) rli[r] = __builtin_amdgcn_rcpf(li_l[crow(r, hi)]);
;   __syncthreads();
;   float* stg = (float*)(lds + wid * 16384);
;   float* Ow = Ob + (long)(wid * QBLK + (lane >> 4)) * LDO + (lane & 15) * 8;
;   bf16_t* OBw = OBh + (long)(wid * QBLK + (lane >> 4)) * DM + (lane & 15) * 8;
;   const float* sl = stg + (lane >> 4) * 128 + (lane & 15) * 8;
; #pragma unroll
;   for (int half = 0; half < 2; ++half) {
; #pragma unroll
;     for (int d = 0; d < 4; ++d)
; #pragma unroll
;       for (int r = 0; r < 16; ++r) stg[crow(r, hi) * 128 + d * 32 + r32] = o[half * 4 + d][r] * rli[r];
;     asm volatile("s_waitcnt lgkmcnt(0)" ::: "memory");
;     if (mode == 0) {
.LBB0_138:
	s_xor_b64 s[8:9], s[34:35], -1
	v_cmp_gt_u32_e32 vcc, 32, v225
	s_and_saveexec_b64 s[6:7], vcc
	ds_write_b32 v234, v144
	s_or_b64 exec, exec, s[6:7]
	s_waitcnt lgkmcnt(0)
	v_lshl_add_u32 v132, v224, 4, s80
	ds_read_b128 v[128:131], v132
	ds_read_b128 v[148:151], v132 offset:32
	s_lshl_b32 s1, s82, 14
	s_add_i32 s1, s1, 0
	s_andn2_b64 vcc, exec, s[8:9]
	s_waitcnt lgkmcnt(0)
	v_rcp_f32_e32 v146, v128
	v_rcp_f32_e32 v143, v129
	v_rcp_f32_e32 v140, v130
	v_rcp_f32_e32 v137, v131
	ds_read_b128 v[128:131], v132 offset:64
	v_rcp_f32_e32 v141, v150
	v_rcp_f32_e32 v138, v151
	ds_read_b128 v[150:153], v132 offset:96
	v_lshrrev_b32_e32 v132, 4, v225
	v_rcp_f32_e32 v135, v148
	s_waitcnt lgkmcnt(0)
	v_rcp_f32_e32 v148, v128
	v_or_b32_e32 v128, s83, v132
	v_rcp_f32_e32 v147, v129
	v_ashrrev_i32_e32 v129, 31, v128
	v_rcp_f32_e32 v144, v149
	v_rcp_f32_e32 v145, v130
	v_rcp_f32_e32 v142, v131
	v_lshlrev_b64 v[130:131], 13, v[128:129]
	v_and_b32_e32 v149, 0x78, v217
	v_lshlrev_b64 v[128:129], 12, v[128:129]
	v_rcp_f32_e32 v139, v150
	v_rcp_f32_e32 v136, v151
	v_lshl_add_u64 v[128:129], s[42:43], 0, v[128:129]
	v_lshlrev_b32_e32 v150, 1, v149
	v_mov_b32_e32 v151, v211
	v_lshlrev_b32_e32 v210, 2, v149
	v_lshl_add_u64 v[128:129], v[128:129], 0, v[150:151]
	v_lshlrev_b32_e32 v149, 11, v224
	v_lshlrev_b32_e32 v150, 2, v213
	v_add3_u32 v149, s1, v149, v150
	v_mul_f32_e32 v96, v96, v146
	v_mul_f32_e32 v112, v112, v146
	v_mul_f32_e32 v80, v80, v146
	v_mul_f32_e32 v64, v64, v146
	s_waitcnt vmcnt(0)
	s_barrier
	v_mul_f32_e32 v97, v97, v143
	ds_write2_b32 v149, v96, v112 offset1:32
	v_mul_f32_e32 v96, v113, v143
	v_mul_f32_e32 v81, v81, v143
	ds_write2_b32 v149, v80, v64 offset0:64 offset1:96
	v_mul_f32_e32 v64, v65, v143
	v_mul_f32_e32 v98, v98, v140
	ds_write2_b32 v149, v97, v96 offset0:128 offset1:160
	v_mul_f32_e32 v97, v114, v140
	v_add_u32_e32 v96, 0x400, v149
	v_mul_f32_e32 v82, v82, v140
	ds_write2_b32 v149, v81, v64 offset0:192 offset1:224
	v_mul_f32_e32 v64, v66, v140
	v_mul_f32_e32 v99, v99, v137
	ds_write2_b32 v96, v98, v97 offset1:32
	v_mul_f32_e32 v97, v115, v137
	v_mul_f32_e32 v83, v83, v137
	ds_write2_b32 v96, v82, v64 offset0:64 offset1:96
	v_mul_f32_e32 v64, v67, v137
	v_mul_f32_e32 v100, v100, v135
	ds_write2_b32 v96, v99, v97 offset0:128 offset1:160
	v_mul_f32_e32 v98, v116, v135
	v_add_u32_e32 v97, 0x1000, v149
	v_mul_f32_e32 v84, v84, v135
	ds_write2_b32 v96, v83, v64 offset0:192 offset1:224
	v_mul_f32_e32 v64, v68, v135
	v_mul_f32_e32 v101, v101, v144
	ds_write2_b32 v97, v100, v98 offset1:32
	v_mul_f32_e32 v98, v117, v144
	v_mul_f32_e32 v85, v85, v144
	ds_write2_b32 v97, v84, v64 offset0:64 offset1:96
	v_mul_f32_e32 v64, v69, v144
	v_mul_f32_e32 v102, v102, v141
	ds_write2_b32 v97, v101, v98 offset0:128 offset1:160
	v_mul_f32_e32 v99, v118, v141
	v_add_u32_e32 v98, 0x1400, v149
	v_mul_f32_e32 v86, v86, v141
	ds_write2_b32 v97, v85, v64 offset0:192 offset1:224
	v_mul_f32_e32 v64, v70, v141
	v_mul_f32_e32 v103, v103, v138
	ds_write2_b32 v98, v102, v99 offset1:32
	v_mul_f32_e32 v99, v119, v138
	v_mul_f32_e32 v87, v87, v138
	ds_write2_b32 v98, v86, v64 offset0:64 offset1:96
	v_mul_f32_e32 v64, v71, v138
	v_mul_f32_e32 v104, v104, v148
	ds_write2_b32 v98, v103, v99 offset0:128 offset1:160
	v_mul_f32_e32 v100, v120, v148
	v_add_u32_e32 v99, 0x2000, v149
	v_mul_f32_e32 v88, v88, v148
	ds_write2_b32 v98, v87, v64 offset0:192 offset1:224
	v_mul_f32_e32 v64, v72, v148
	v_mul_f32_e32 v105, v105, v147
	ds_write2_b32 v99, v104, v100 offset1:32
	v_mul_f32_e32 v100, v121, v147
	v_mul_f32_e32 v89, v89, v147
	ds_write2_b32 v99, v88, v64 offset0:64 offset1:96
	v_mul_f32_e32 v64, v73, v147
	v_rcp_f32_e32 v134, v152
	v_mul_f32_e32 v106, v106, v145
	ds_write2_b32 v99, v105, v100 offset0:128 offset1:160
	v_mul_f32_e32 v101, v122, v145
	v_add_u32_e32 v100, 0x2400, v149
	v_mul_f32_e32 v90, v90, v145
	ds_write2_b32 v99, v89, v64 offset0:192 offset1:224
	v_mul_f32_e32 v64, v74, v145
	v_rcp_f32_e32 v133, v153
	v_mul_f32_e32 v107, v107, v142
	ds_write2_b32 v100, v106, v101 offset1:32
	v_mul_f32_e32 v101, v123, v142
	v_mul_f32_e32 v91, v91, v142
	ds_write2_b32 v100, v90, v64 offset0:64 offset1:96
	v_mul_f32_e32 v64, v75, v142
	v_mul_f32_e32 v108, v108, v139
	ds_write2_b32 v100, v107, v101 offset0:128 offset1:160
	v_mul_f32_e32 v102, v124, v139
	v_add_u32_e32 v101, 0x3000, v149
	v_mul_f32_e32 v92, v92, v139
	ds_write2_b32 v100, v91, v64 offset0:192 offset1:224
	v_mul_f32_e32 v64, v76, v139
	v_mul_f32_e32 v109, v109, v136
	ds_write2_b32 v101, v108, v102 offset1:32
	v_mul_f32_e32 v102, v125, v136
	v_mul_f32_e32 v93, v93, v136
	ds_write2_b32 v101, v92, v64 offset0:64 offset1:96
	v_mul_f32_e32 v64, v77, v136
	v_mul_f32_e32 v110, v110, v134
	ds_write2_b32 v101, v109, v102 offset0:128 offset1:160
	v_mul_f32_e32 v103, v126, v134
	v_add_u32_e32 v102, 0x3400, v149
	v_mul_f32_e32 v94, v94, v134
	ds_write2_b32 v101, v93, v64 offset0:192 offset1:224
	v_mul_f32_e32 v64, v78, v134
	v_mul_f32_e32 v111, v111, v133
	ds_write2_b32 v102, v110, v103 offset1:32
	v_mul_f32_e32 v103, v127, v133
	v_mul_f32_e32 v95, v95, v133
	ds_write2_b32 v102, v94, v64 offset0:64 offset1:96
	v_mul_f32_e32 v64, v79, v133
	v_lshlrev_b32_e32 v132, 9, v132
	ds_write2_b32 v102, v111, v103 offset0:128 offset1:160
	ds_write2_b32 v102, v95, v64 offset0:192 offset1:224
	v_add3_u32 v132, s1, v132, v210
	s_waitcnt lgkmcnt(0)
	ds_read_b128 v[68:71], v132
	ds_read_b128 v[64:67], v132 offset:16
	v_lshl_add_u64 v[130:131], s[30:31], 0, v[130:131]
	v_cndmask_b32_e64 v72, 0, 1, s[8:9]
	v_lshl_add_u64 v[130:131], v[130:131], 0, v[210:211]
	v_cmp_ne_u32_e64 s[6:7], 1, v72
	s_mov_b64 s[10:11], -1
	s_cbranch_vccnz .LBB0_142
; __device__ __forceinline__ float bf_lo(unsigned v) { return __uint_as_float(v << 16); }
; __device__ __forceinline__ float bf_hi(unsigned v) { return __uint_as_float(v & 0xffff0000u); }
; __device__ __forceinline__ void attn_pass(const bf16_t* __restrict__ Qb, const bf16_t* __restrict__ Kh, const bf16_t* __restrict__ Vh,
;                                           float* Ob, int mode, float lam, int qpos0, int seq, char* lds, const int wv, bf16_t* OBh) {
;     ...
;       for (int k = 0; k < 8; ++k) { const f32x4 v0 = *(const f32x4*)(sl + k * 512), v1 = *(const f32x4*)(sl + k * 512 + 4);
;         const u32x4 pw = *(const u32x4*)(OBw + (long)(4 * k) * DM + half * 128);
;         const f32x4 p0 = {bf_lo(pw.x), bf_hi(pw.x), bf_lo(pw.y), bf_hi(pw.y)}, p1 = {bf_lo(pw.z), bf_hi(pw.z), bf_lo(pw.w), bf_hi(pw.w)};
;         float* gp = Ow + (long)(4 * k) * LDO + half * 128;
;         *(f32x4*)gp = p0 - lam * v0; *(f32x4*)(gp + 4) = p1 - lam * v1; }
	global_load_dwordx4 v[88:91], v[128:129], off
	v_add_co_u32_e32 v92, vcc, s69, v128
	s_nop 1
	v_addc_co_u32_e32 v93, vcc, 0, v129, vcc
	global_load_dwordx4 v[92:95], v[92:93], off
	v_add_co_u32_e32 v104, vcc, s91, v128
	s_nop 1
	v_addc_co_u32_e32 v105, vcc, 0, v129, vcc
	global_load_dwordx4 v[104:107], v[104:105], off
	v_add_co_u32_e32 v108, vcc, s76, v128
	s_nop 1
	v_addc_co_u32_e32 v109, vcc, 0, v129, vcc
	global_load_dwordx4 v[108:111], v[108:109], off
	v_add_co_u32_e32 v112, vcc, s67, v128
	s_nop 1
	v_addc_co_u32_e32 v113, vcc, 0, v129, vcc
	global_load_dwordx4 v[112:115], v[112:113], off
	v_add_co_u32_e32 v116, vcc, s75, v128
	s_nop 1
	v_addc_co_u32_e32 v117, vcc, 0, v129, vcc
	global_load_dwordx4 v[116:119], v[116:117], off
	v_add_co_u32_e32 v120, vcc, s90, v128
	s_nop 1
	v_addc_co_u32_e32 v121, vcc, 0, v129, vcc
	global_load_dwordx4 v[120:123], v[120:121], off
	v_add_co_u32_e32 v124, vcc, s33, v128
	s_nop 1
	v_addc_co_u32_e32 v125, vcc, 0, v129, vcc
	global_load_dwordx4 v[124:127], v[124:125], off
	s_xor_b32 s17, s5, 0x80000000
	s_xor_b32 s16, s4, 0x80000000
	s_mov_b64 s[10:11], 0
	s_waitcnt vmcnt(0)
	v_mov_b32_e32 v72, v88
	v_mov_b32_e32 v73, v89
	v_mov_b32_e32 v74, v90
	v_mov_b32_e32 v75, v91
	v_lshlrev_b32_e32 v76, 16, v72
	v_and_b32_e32 v77, 0xffff0000, v72
	v_lshlrev_b32_e32 v72, 16, v73
	v_and_b32_e32 v73, 0xffff0000, v73
	v_lshlrev_b32_e32 v78, 16, v74
	v_and_b32_e32 v79, 0xffff0000, v74
	v_lshlrev_b32_e32 v80, 16, v75
	v_and_b32_e32 v81, 0xffff0000, v75
	s_waitcnt lgkmcnt(1)
	v_pk_fma_f32 v[74:75], s[16:17], v[70:71], v[72:73]
	v_pk_fma_f32 v[72:73], s[40:41], v[68:69], v[76:77] neg_lo:[1,0,0] neg_hi:[1,0,0]
	global_store_dwordx4 v[130:131], v[72:75], off
	s_waitcnt lgkmcnt(0)
	s_nop 0
	v_pk_fma_f32 v[74:75], s[16:17], v[66:67], v[80:81]
	v_pk_fma_f32 v[72:73], s[40:41], v[64:65], v[78:79] neg_lo:[1,0,0] neg_hi:[1,0,0]
	v_add_co_u32_e32 v80, vcc, s69, v128
	global_store_dwordx4 v[130:131], v[72:75], off offset:16
	s_nop 0
	v_addc_co_u32_e32 v81, vcc, 0, v129, vcc
	ds_read_b128 v[72:75], v132 offset:2048
	ds_read_b128 v[76:79], v132 offset:2064
	v_mov_b32_e32 v80, v92
	v_mov_b32_e32 v81, v93
	v_mov_b32_e32 v82, v94
	v_mov_b32_e32 v83, v95
	v_lshlrev_b32_e32 v84, 16, v80
	v_and_b32_e32 v85, 0xffff0000, v80
	v_lshlrev_b32_e32 v80, 16, v81
	v_and_b32_e32 v81, 0xffff0000, v81
	s_waitcnt lgkmcnt(1)
	v_pk_fma_f32 v[74:75], s[16:17], v[74:75], v[80:81]
	v_add_co_u32_e32 v80, vcc, s91, v130
	v_lshlrev_b32_e32 v86, 16, v82
	v_and_b32_e32 v87, 0xffff0000, v82
	v_lshlrev_b32_e32 v82, 16, v83
	v_and_b32_e32 v83, 0xffff0000, v83
	v_pk_fma_f32 v[72:73], s[40:41], v[72:73], v[84:85] neg_lo:[1,0,0] neg_hi:[1,0,0]
	v_addc_co_u32_e32 v81, vcc, 0, v131, vcc
	global_store_dwordx4 v[80:81], v[72:75], off
	s_waitcnt lgkmcnt(0)
	s_nop 0
	v_pk_fma_f32 v[74:75], s[16:17], v[78:79], v[82:83]
	v_pk_fma_f32 v[72:73], s[40:41], v[76:77], v[86:87] neg_lo:[1,0,0] neg_hi:[1,0,0]
	global_store_dwordx4 v[80:81], v[72:75], off offset:16
	v_add_co_u32_e32 v80, vcc, s91, v128
	ds_read_b128 v[72:75], v132 offset:4096
	ds_read_b128 v[76:79], v132 offset:4112
	v_addc_co_u32_e32 v81, vcc, 0, v129, vcc
	v_mov_b32_e32 v80, v104
	v_mov_b32_e32 v81, v105
	v_mov_b32_e32 v82, v106
	v_mov_b32_e32 v83, v107
	v_lshlrev_b32_e32 v84, 16, v80
	v_and_b32_e32 v85, 0xffff0000, v80
	v_lshlrev_b32_e32 v80, 16, v81
	v_and_b32_e32 v81, 0xffff0000, v81
	s_waitcnt lgkmcnt(1)
	v_pk_fma_f32 v[74:75], s[16:17], v[74:75], v[80:81]
	v_add_co_u32_e32 v80, vcc, s67, v130
	v_lshlrev_b32_e32 v86, 16, v82
	v_and_b32_e32 v87, 0xffff0000, v82
	v_lshlrev_b32_e32 v82, 16, v83
	v_and_b32_e32 v83, 0xffff0000, v83
	v_pk_fma_f32 v[72:73], s[40:41], v[72:73], v[84:85] neg_lo:[1,0,0] neg_hi:[1,0,0]
	v_addc_co_u32_e32 v81, vcc, 0, v131, vcc
	global_store_dwordx4 v[80:81], v[72:75], off
	s_waitcnt lgkmcnt(0)
	s_nop 0
	v_pk_fma_f32 v[74:75], s[16:17], v[78:79], v[82:83]
	v_pk_fma_f32 v[72:73], s[40:41], v[76:77], v[86:87] neg_lo:[1,0,0] neg_hi:[1,0,0]
	global_store_dwordx4 v[80:81], v[72:75], off offset:16
	v_add_co_u32_e32 v80, vcc, s76, v128
	ds_read_b128 v[72:75], v132 offset:6144
	ds_read_b128 v[76:79], v132 offset:6160
	v_addc_co_u32_e32 v81, vcc, 0, v129, vcc
	v_mov_b32_e32 v80, v108
	v_mov_b32_e32 v81, v109
	v_mov_b32_e32 v82, v110
	v_mov_b32_e32 v83, v111
	v_lshlrev_b32_e32 v84, 16, v80
	v_and_b32_e32 v85, 0xffff0000, v80
	v_lshlrev_b32_e32 v80, 16, v81
	v_and_b32_e32 v81, 0xffff0000, v81
	s_waitcnt lgkmcnt(1)
; __device__ __forceinline__ float bf_lo(unsigned v) { return __uint_as_float(v << 16); }
; __device__ __forceinline__ float bf_hi(unsigned v) { return __uint_as_float(v & 0xffff0000u); }
; __device__ __forceinline__ void attn_pass(const bf16_t* __restrict__ Qb, const bf16_t* __restrict__ Kh, const bf16_t* __restrict__ Vh,
;                                           float* Ob, int mode, float lam, int qpos0, int seq, char* lds, const int wv, bf16_t* OBh) {
;     ...
;       for (int k = 0; k < 8; ++k) { const f32x4 v0 = *(const f32x4*)(sl + k * 512), v1 = *(const f32x4*)(sl + k * 512 + 4);
;         const u32x4 pw = *(const u32x4*)(OBw + (long)(4 * k) * DM + half * 128);
;         const f32x4 p0 = {bf_lo(pw.x), bf_hi(pw.x), bf_lo(pw.y), bf_hi(pw.y)}, p1 = {bf_lo(pw.z), bf_hi(pw.z), bf_lo(pw.w), bf_hi(pw.w)};
;         float* gp = Ow + (long)(4 * k) * LDO + half * 128;
;         *(f32x4*)gp = p0 - lam * v0; *(f32x4*)(gp + 4) = p1 - lam * v1; }
	v_pk_fma_f32 v[74:75], s[16:17], v[74:75], v[80:81]
	v_add_co_u32_e32 v80, vcc, s90, v130
	v_lshlrev_b32_e32 v86, 16, v82
	v_and_b32_e32 v87, 0xffff0000, v82
	v_lshlrev_b32_e32 v82, 16, v83
	v_and_b32_e32 v83, 0xffff0000, v83
	v_pk_fma_f32 v[72:73], s[40:41], v[72:73], v[84:85] neg_lo:[1,0,0] neg_hi:[1,0,0]
	v_addc_co_u32_e32 v81, vcc, 0, v131, vcc
	global_store_dwordx4 v[80:81], v[72:75], off
	s_waitcnt lgkmcnt(0)
	s_nop 0
	v_pk_fma_f32 v[74:75], s[16:17], v[78:79], v[82:83]
	v_pk_fma_f32 v[72:73], s[40:41], v[76:77], v[86:87] neg_lo:[1,0,0] neg_hi:[1,0,0]
	global_store_dwordx4 v[80:81], v[72:75], off offset:16
	v_add_co_u32_e32 v80, vcc, s67, v128
	ds_read_b128 v[72:75], v132 offset:8192
	ds_read_b128 v[76:79], v132 offset:8208
	v_addc_co_u32_e32 v81, vcc, 0, v129, vcc
	v_mov_b32_e32 v80, v112
	v_mov_b32_e32 v81, v113
	v_mov_b32_e32 v82, v114
	v_mov_b32_e32 v83, v115
	v_lshlrev_b32_e32 v84, 16, v80
	v_and_b32_e32 v85, 0xffff0000, v80
	v_lshlrev_b32_e32 v80, 16, v81
	v_and_b32_e32 v81, 0xffff0000, v81
	s_waitcnt lgkmcnt(1)
	v_pk_fma_f32 v[74:75], s[16:17], v[74:75], v[80:81]
	v_add_co_u32_e32 v80, vcc, s50, v130
	v_lshlrev_b32_e32 v86, 16, v82
	v_and_b32_e32 v87, 0xffff0000, v82
	v_lshlrev_b32_e32 v82, 16, v83
	v_and_b32_e32 v83, 0xffff0000, v83
	v_pk_fma_f32 v[72:73], s[40:41], v[72:73], v[84:85] neg_lo:[1,0,0] neg_hi:[1,0,0]
	v_addc_co_u32_e32 v81, vcc, 0, v131, vcc
	global_store_dwordx4 v[80:81], v[72:75], off
	s_waitcnt lgkmcnt(0)
	s_nop 0
	v_pk_fma_f32 v[74:75], s[16:17], v[78:79], v[82:83]
	v_pk_fma_f32 v[72:73], s[40:41], v[76:77], v[86:87] neg_lo:[1,0,0] neg_hi:[1,0,0]
	global_store_dwordx4 v[80:81], v[72:75], off offset:16
	v_add_co_u32_e32 v80, vcc, s75, v128
	ds_read_b128 v[72:75], v132 offset:10240
	ds_read_b128 v[76:79], v132 offset:10256
	v_addc_co_u32_e32 v81, vcc, 0, v129, vcc
	v_mov_b32_e32 v80, v116
	v_mov_b32_e32 v81, v117
	v_mov_b32_e32 v82, v118
	v_mov_b32_e32 v83, v119
	v_lshlrev_b32_e32 v84, 16, v80
	v_and_b32_e32 v85, 0xffff0000, v80
	v_lshlrev_b32_e32 v80, 16, v81
	v_and_b32_e32 v81, 0xffff0000, v81
	s_waitcnt lgkmcnt(1)
	v_pk_fma_f32 v[74:75], s[16:17], v[74:75], v[80:81]
	v_add_co_u32_e32 v80, vcc, s51, v130
	v_lshlrev_b32_e32 v86, 16, v82
	v_and_b32_e32 v87, 0xffff0000, v82
	v_lshlrev_b32_e32 v82, 16, v83
	v_and_b32_e32 v83, 0xffff0000, v83
	v_pk_fma_f32 v[72:73], s[40:41], v[72:73], v[84:85] neg_lo:[1,0,0] neg_hi:[1,0,0]
	v_addc_co_u32_e32 v81, vcc, 0, v131, vcc
	global_store_dwordx4 v[80:81], v[72:75], off
	s_waitcnt lgkmcnt(0)
	s_nop 0
	v_pk_fma_f32 v[74:75], s[16:17], v[78:79], v[82:83]
	v_pk_fma_f32 v[72:73], s[40:41], v[76:77], v[86:87] neg_lo:[1,0,0] neg_hi:[1,0,0]
	global_store_dwordx4 v[80:81], v[72:75], off offset:16
	v_add_co_u32_e32 v80, vcc, s90, v128
	ds_read_b128 v[72:75], v132 offset:12288
	ds_read_b128 v[76:79], v132 offset:12304
	v_addc_co_u32_e32 v81, vcc, 0, v129, vcc
	v_mov_b32_e32 v80, v120
	v_mov_b32_e32 v81, v121
	v_mov_b32_e32 v82, v122
	v_mov_b32_e32 v83, v123
	v_lshlrev_b32_e32 v84, 16, v80
	v_and_b32_e32 v85, 0xffff0000, v80
	v_lshlrev_b32_e32 v80, 16, v81
	v_and_b32_e32 v81, 0xffff0000, v81
	s_waitcnt lgkmcnt(1)
	v_pk_fma_f32 v[74:75], s[16:17], v[74:75], v[80:81]
	v_add_co_u32_e32 v80, vcc, s78, v130
	v_lshlrev_b32_e32 v86, 16, v82
	v_and_b32_e32 v87, 0xffff0000, v82
	v_lshlrev_b32_e32 v82, 16, v83
	v_and_b32_e32 v83, 0xffff0000, v83
	v_pk_fma_f32 v[72:73], s[40:41], v[72:73], v[84:85] neg_lo:[1,0,0] neg_hi:[1,0,0]
	v_addc_co_u32_e32 v81, vcc, 0, v131, vcc
	global_store_dwordx4 v[80:81], v[72:75], off
	s_waitcnt lgkmcnt(0)
	s_nop 0
	v_pk_fma_f32 v[74:75], s[16:17], v[78:79], v[82:83]
	v_pk_fma_f32 v[72:73], s[40:41], v[76:77], v[86:87] neg_lo:[1,0,0] neg_hi:[1,0,0]
	global_store_dwordx4 v[80:81], v[72:75], off offset:16
	v_add_co_u32_e32 v80, vcc, s33, v128
	ds_read_b128 v[72:75], v132 offset:14336
	ds_read_b128 v[76:79], v132 offset:14352
	v_addc_co_u32_e32 v81, vcc, 0, v129, vcc
	v_mov_b32_e32 v80, v124
	v_mov_b32_e32 v81, v125
	v_mov_b32_e32 v82, v126
	v_mov_b32_e32 v83, v127
	v_lshlrev_b32_e32 v84, 16, v80
	v_and_b32_e32 v85, 0xffff0000, v80
	v_lshlrev_b32_e32 v80, 16, v81
	v_and_b32_e32 v81, 0xffff0000, v81
	s_waitcnt lgkmcnt(1)
	v_pk_fma_f32 v[74:75], s[16:17], v[74:75], v[80:81]
	v_add_co_u32_e32 v80, vcc, 0x38000, v130
	v_lshlrev_b32_e32 v86, 16, v82
	v_and_b32_e32 v87, 0xffff0000, v82
	v_lshlrev_b32_e32 v82, 16, v83
	v_and_b32_e32 v83, 0xffff0000, v83
	v_pk_fma_f32 v[72:73], s[40:41], v[72:73], v[84:85] neg_lo:[1,0,0] neg_hi:[1,0,0]
	v_addc_co_u32_e32 v81, vcc, 0, v131, vcc
	global_store_dwordx4 v[80:81], v[72:75], off
	s_waitcnt lgkmcnt(0)
	s_nop 0
	v_pk_fma_f32 v[74:75], s[16:17], v[78:79], v[82:83]
	v_pk_fma_f32 v[72:73], s[40:41], v[76:77], v[86:87] neg_lo:[1,0,0] neg_hi:[1,0,0]
	global_store_dwordx4 v[80:81], v[72:75], off offset:16

; __device__ __forceinline__ unsigned cvt_pk_bf16(float lo, float hi) { unsigned r; asm volatile("v_cvt_pk_bf16_f32 %0, %1, %2" : "=v"(r) : "v"(lo), "v"(hi)); return r; }
; __device__ __forceinline__ float bf_lo(unsigned v) { return __uint_as_float(v << 16); }
; __device__ __forceinline__ float bf_hi(unsigned v) { return __uint_as_float(v & 0xffff0000u); }
; __device__ __forceinline__ int crow(int r, int hi) { return (r & 3) + 8 * (r >> 2) + 4 * hi; }
; __device__ __forceinline__ void attn_pass(const bf16_t* __restrict__ Qb, const bf16_t* __restrict__ Kh, const bf16_t* __restrict__ Vh,
;                                           float* Ob, int mode, float lam, int qpos0, int seq, char* lds, const int wv, bf16_t* OBh) {
;     ...
;     for (int d = 0; d < 4; ++d)
; #pragma unroll
;       for (int r = 0; r < 16; ++r) stg[crow(r, hi) * 128 + d * 32 + r32] = o[half * 4 + d][r] * rli[r];
;     asm volatile("s_waitcnt lgkmcnt(0)" ::: "memory");
;     if (mode == 0) {
; #pragma unroll
;       for (int k = 0; k < 8; ++k) { const f32x4 v0 = *(const f32x4*)(sl + k * 512), v1 = *(const f32x4*)(sl + k * 512 + 4);
;         u32x4 w; w.x = cvt_pk_bf16(v0[0], v0[1]); w.y = cvt_pk_bf16(v0[2], v0[3]); w.z = cvt_pk_bf16(v1[0], v1[1]); w.w = cvt_pk_bf16(v1[2], v1[3]);
;         *(u32x4*)(OBw + (long)(4 * k) * DM + half * 128) = w; }
;     } else {
; #pragma unroll
;       for (int k = 0; k < 8; ++k) { const f32x4 v0 = *(const f32x4*)(sl + k * 512), v1 = *(const f32x4*)(sl + k * 512 + 4);
;         const u32x4 pw = *(const u32x4*)(OBw + (long)(4 * k) * DM + half * 128);
;         const f32x4 p0 = {bf_lo(pw.x), bf_hi(pw.x), bf_lo(pw.y), bf_hi(pw.y)}, p1 = {bf_lo(pw.z), bf_hi(pw.z), bf_lo(pw.w), bf_hi(pw.w)};
;         float* gp = Ow + (long)(4 * k) * LDO + half * 128;
;         *(f32x4*)gp = p0 - lam * v0; *(f32x4*)(gp + 4) = p1 - lam * v1; }
.LBB0_144:
	v_mul_f32_e32 v48, v48, v146
	v_mul_f32_e32 v32, v32, v146
	v_mul_f32_e32 v16, v16, v146
	v_mul_f32_e32 v0, v0, v146
	s_waitcnt lgkmcnt(0)
	v_mul_f32_e32 v49, v49, v143
	ds_write2_b32 v149, v48, v32 offset1:32
	v_mul_f32_e32 v32, v33, v143
	v_mul_f32_e32 v17, v17, v143
	ds_write2_b32 v149, v16, v0 offset0:64 offset1:96
	v_mul_f32_e32 v0, v1, v143
	v_mul_f32_e32 v50, v50, v140
	ds_write2_b32 v149, v49, v32 offset0:128 offset1:160
	v_mul_f32_e32 v32, v34, v140
	v_mul_f32_e32 v18, v18, v140
	ds_write2_b32 v149, v17, v0 offset0:192 offset1:224
	v_mul_f32_e32 v0, v2, v140
	v_mul_f32_e32 v51, v51, v137
	ds_write2_b32 v96, v50, v32 offset1:32
	v_mul_f32_e32 v32, v35, v137
	v_mul_f32_e32 v19, v19, v137
	ds_write2_b32 v96, v18, v0 offset0:64 offset1:96
	v_mul_f32_e32 v0, v3, v137
	v_mul_f32_e32 v52, v52, v135
	ds_write2_b32 v96, v51, v32 offset0:128 offset1:160
	v_mul_f32_e32 v32, v36, v135
	v_mul_f32_e32 v20, v20, v135
	ds_write2_b32 v96, v19, v0 offset0:192 offset1:224
	v_mul_f32_e32 v0, v4, v135
	v_mul_f32_e32 v53, v53, v144
	ds_write2_b32 v97, v52, v32 offset1:32
	v_mul_f32_e32 v32, v37, v144
	v_mul_f32_e32 v21, v21, v144
	ds_write2_b32 v97, v20, v0 offset0:64 offset1:96
	v_mul_f32_e32 v0, v5, v144
	v_mul_f32_e32 v54, v54, v141
	ds_write2_b32 v97, v53, v32 offset0:128 offset1:160
	v_mul_f32_e32 v32, v38, v141
	v_mul_f32_e32 v22, v22, v141
	ds_write2_b32 v97, v21, v0 offset0:192 offset1:224
	v_mul_f32_e32 v0, v6, v141
	v_mul_f32_e32 v55, v55, v138
	ds_write2_b32 v98, v54, v32 offset1:32
	v_mul_f32_e32 v32, v39, v138
	v_mul_f32_e32 v23, v23, v138
	ds_write2_b32 v98, v22, v0 offset0:64 offset1:96
	v_mul_f32_e32 v0, v7, v138
	v_mul_f32_e32 v56, v56, v148
	ds_write2_b32 v98, v55, v32 offset0:128 offset1:160
	v_mul_f32_e32 v32, v40, v148
	v_mul_f32_e32 v24, v24, v148
	ds_write2_b32 v98, v23, v0 offset0:192 offset1:224
	v_mul_f32_e32 v0, v8, v148
	v_mul_f32_e32 v57, v57, v147
	ds_write2_b32 v99, v56, v32 offset1:32
	v_mul_f32_e32 v32, v41, v147
	v_mul_f32_e32 v25, v25, v147
	ds_write2_b32 v99, v24, v0 offset0:64 offset1:96
	v_mul_f32_e32 v0, v9, v147
	v_mul_f32_e32 v58, v58, v145
	ds_write2_b32 v99, v57, v32 offset0:128 offset1:160
	v_mul_f32_e32 v32, v42, v145
	v_mul_f32_e32 v26, v26, v145
	ds_write2_b32 v99, v25, v0 offset0:192 offset1:224
	v_mul_f32_e32 v0, v10, v145
	v_mul_f32_e32 v59, v59, v142
	ds_write2_b32 v100, v58, v32 offset1:32
	v_mul_f32_e32 v32, v43, v142
	v_mul_f32_e32 v27, v27, v142
	ds_write2_b32 v100, v26, v0 offset0:64 offset1:96
	v_mul_f32_e32 v0, v11, v142
	v_mul_f32_e32 v60, v60, v139
	ds_write2_b32 v100, v59, v32 offset0:128 offset1:160
	v_mul_f32_e32 v32, v44, v139
	v_mul_f32_e32 v28, v28, v139
	ds_write2_b32 v100, v27, v0 offset0:192 offset1:224
	v_mul_f32_e32 v0, v12, v139
	v_mul_f32_e32 v61, v61, v136
	ds_write2_b32 v101, v60, v32 offset1:32
	v_mul_f32_e32 v32, v45, v136
	v_mul_f32_e32 v29, v29, v136
	ds_write2_b32 v101, v28, v0 offset0:64 offset1:96
	v_mul_f32_e32 v0, v13, v136
	v_mul_f32_e32 v62, v62, v134
	ds_write2_b32 v101, v61, v32 offset0:128 offset1:160
	v_mul_f32_e32 v32, v46, v134
	v_mul_f32_e32 v30, v30, v134
	ds_write2_b32 v101, v29, v0 offset0:192 offset1:224
	v_mul_f32_e32 v0, v14, v134
	v_mul_f32_e32 v63, v63, v133
	ds_write2_b32 v102, v62, v32 offset1:32
	v_mul_f32_e32 v32, v47, v133
	v_mul_f32_e32 v31, v31, v133
	ds_write2_b32 v102, v30, v0 offset0:64 offset1:96
	v_mul_f32_e32 v0, v15, v133
	ds_write2_b32 v102, v63, v32 offset0:128 offset1:160
	ds_write2_b32 v102, v31, v0 offset0:192 offset1:224
	s_waitcnt lgkmcnt(0)
	s_and_b64 vcc, exec, s[6:7]
	s_mov_b64 s[6:7], -1
	s_cbranch_vccnz .LBB0_146
	ds_read_b128 v[0:3], v132
	ds_read_b128 v[4:7], v132 offset:16
	global_load_dwordx4 v[88:91], v[128:129], off offset:256
	v_add_co_u32_e32 v92, vcc, s69, v128
	s_nop 1
	v_addc_co_u32_e32 v93, vcc, 0, v129, vcc
	global_load_dwordx4 v[92:95], v[92:93], off offset:256
	v_add_co_u32_e32 v104, vcc, s91, v128
	s_nop 1
	v_addc_co_u32_e32 v105, vcc, 0, v129, vcc
	global_load_dwordx4 v[104:107], v[104:105], off offset:256
	v_add_co_u32_e32 v108, vcc, s76, v128
	s_nop 1
	v_addc_co_u32_e32 v109, vcc, 0, v129, vcc
	global_load_dwordx4 v[108:111], v[108:109], off offset:256
	v_add_co_u32_e32 v112, vcc, s67, v128
	s_nop 1
	v_addc_co_u32_e32 v113, vcc, 0, v129, vcc
	global_load_dwordx4 v[112:115], v[112:113], off offset:256
	v_add_co_u32_e32 v116, vcc, s75, v128
	s_nop 1
	v_addc_co_u32_e32 v117, vcc, 0, v129, vcc
	global_load_dwordx4 v[116:119], v[116:117], off offset:256
	v_add_co_u32_e32 v120, vcc, s90, v128
	s_nop 1
	v_addc_co_u32_e32 v121, vcc, 0, v129, vcc
	global_load_dwordx4 v[120:123], v[120:121], off offset:256
	v_add_co_u32_e32 v124, vcc, s33, v128
	s_nop 1
	v_addc_co_u32_e32 v125, vcc, 0, v129, vcc
	global_load_dwordx4 v[124:127], v[124:125], off offset:256
	s_xor_b32 s7, s5, 0x80000000
	s_xor_b32 s6, s4, 0x80000000
	s_waitcnt vmcnt(0)
	v_mov_b32_e32 v8, v88
	v_mov_b32_e32 v9, v89
	v_mov_b32_e32 v10, v90
	v_mov_b32_e32 v11, v91
	v_lshlrev_b32_e32 v12, 16, v8
	v_and_b32_e32 v13, 0xffff0000, v8
	v_lshlrev_b32_e32 v8, 16, v9
	v_and_b32_e32 v9, 0xffff0000, v9
	v_lshlrev_b32_e32 v14, 16, v10
	v_and_b32_e32 v15, 0xffff0000, v10
	v_lshlrev_b32_e32 v10, 16, v11
	v_and_b32_e32 v11, 0xffff0000, v11
	s_waitcnt lgkmcnt(1)
	v_pk_fma_f32 v[2:3], s[6:7], v[2:3], v[8:9]
	v_pk_fma_f32 v[0:1], s[40:41], v[0:1], v[12:13] neg_lo:[1,0,0] neg_hi:[1,0,0]
	global_store_dwordx4 v[130:131], v[0:3], off offset:512
	v_add_co_u32_e32 v8, vcc, s69, v128
	s_waitcnt lgkmcnt(0)
; __device__ __forceinline__ float bf_lo(unsigned v) { return __uint_as_float(v << 16); }
; __device__ __forceinline__ float bf_hi(unsigned v) { return __uint_as_float(v & 0xffff0000u); }
; __device__ __forceinline__ void attn_pass(const bf16_t* __restrict__ Qb, const bf16_t* __restrict__ Kh, const bf16_t* __restrict__ Vh,
;                                           float* Ob, int mode, float lam, int qpos0, int seq, char* lds, const int wv, bf16_t* OBh) {
;     ...
;       for (int k = 0; k < 8; ++k) { const f32x4 v0 = *(const f32x4*)(sl + k * 512), v1 = *(const f32x4*)(sl + k * 512 + 4);
;         const u32x4 pw = *(const u32x4*)(OBw + (long)(4 * k) * DM + half * 128);
;         const f32x4 p0 = {bf_lo(pw.x), bf_hi(pw.x), bf_lo(pw.y), bf_hi(pw.y)}, p1 = {bf_lo(pw.z), bf_hi(pw.z), bf_lo(pw.w), bf_hi(pw.w)};
;         float* gp = Ow + (long)(4 * k) * LDO + half * 128;
;         *(f32x4*)gp = p0 - lam * v0; *(f32x4*)(gp + 4) = p1 - lam * v1; }
	v_pk_fma_f32 v[2:3], s[6:7], v[6:7], v[10:11]
	v_pk_fma_f32 v[0:1], s[40:41], v[4:5], v[14:15] neg_lo:[1,0,0] neg_hi:[1,0,0]
	global_store_dwordx4 v[130:131], v[0:3], off offset:528
	v_addc_co_u32_e32 v9, vcc, 0, v129, vcc
	ds_read_b128 v[0:3], v132 offset:2048
	ds_read_b128 v[4:7], v132 offset:2064
	v_mov_b32_e32 v8, v92
	v_mov_b32_e32 v9, v93
	v_mov_b32_e32 v10, v94
	v_mov_b32_e32 v11, v95
	v_lshlrev_b32_e32 v12, 16, v8
	v_and_b32_e32 v13, 0xffff0000, v8
	v_lshlrev_b32_e32 v8, 16, v9
	v_and_b32_e32 v9, 0xffff0000, v9
	s_waitcnt lgkmcnt(1)
	v_pk_fma_f32 v[2:3], s[6:7], v[2:3], v[8:9]
	v_add_co_u32_e32 v8, vcc, s91, v130
	v_lshlrev_b32_e32 v14, 16, v10
	v_and_b32_e32 v15, 0xffff0000, v10
	v_lshlrev_b32_e32 v10, 16, v11
	v_and_b32_e32 v11, 0xffff0000, v11
	v_pk_fma_f32 v[0:1], s[40:41], v[0:1], v[12:13] neg_lo:[1,0,0] neg_hi:[1,0,0]
	v_addc_co_u32_e32 v9, vcc, 0, v131, vcc
	global_store_dwordx4 v[8:9], v[0:3], off offset:512
	s_waitcnt lgkmcnt(0)
	s_nop 0
	v_pk_fma_f32 v[2:3], s[6:7], v[6:7], v[10:11]
	v_pk_fma_f32 v[0:1], s[40:41], v[4:5], v[14:15] neg_lo:[1,0,0] neg_hi:[1,0,0]
	global_store_dwordx4 v[8:9], v[0:3], off offset:528
	v_add_co_u32_e32 v8, vcc, s91, v128
	ds_read_b128 v[0:3], v132 offset:4096
	ds_read_b128 v[4:7], v132 offset:4112
	v_addc_co_u32_e32 v9, vcc, 0, v129, vcc
	v_mov_b32_e32 v8, v104
	v_mov_b32_e32 v9, v105
	v_mov_b32_e32 v10, v106
	v_mov_b32_e32 v11, v107
	v_lshlrev_b32_e32 v12, 16, v8
	v_and_b32_e32 v13, 0xffff0000, v8
	v_lshlrev_b32_e32 v8, 16, v9
	v_and_b32_e32 v9, 0xffff0000, v9
	s_waitcnt lgkmcnt(1)
	v_pk_fma_f32 v[2:3], s[6:7], v[2:3], v[8:9]
	v_add_co_u32_e32 v8, vcc, s67, v130
	v_lshlrev_b32_e32 v14, 16, v10
	v_and_b32_e32 v15, 0xffff0000, v10
	v_lshlrev_b32_e32 v10, 16, v11
	v_and_b32_e32 v11, 0xffff0000, v11
	v_pk_fma_f32 v[0:1], s[40:41], v[0:1], v[12:13] neg_lo:[1,0,0] neg_hi:[1,0,0]
	v_addc_co_u32_e32 v9, vcc, 0, v131, vcc
	global_store_dwordx4 v[8:9], v[0:3], off offset:512
	s_waitcnt lgkmcnt(0)
	s_nop 0
	v_pk_fma_f32 v[2:3], s[6:7], v[6:7], v[10:11]
	v_pk_fma_f32 v[0:1], s[40:41], v[4:5], v[14:15] neg_lo:[1,0,0] neg_hi:[1,0,0]
	global_store_dwordx4 v[8:9], v[0:3], off offset:528
	v_add_co_u32_e32 v8, vcc, s76, v128
	ds_read_b128 v[0:3], v132 offset:6144
	ds_read_b128 v[4:7], v132 offset:6160
	v_addc_co_u32_e32 v9, vcc, 0, v129, vcc
	v_mov_b32_e32 v8, v108
	v_mov_b32_e32 v9, v109
	v_mov_b32_e32 v10, v110
	v_mov_b32_e32 v11, v111
	v_lshlrev_b32_e32 v12, 16, v8
	v_and_b32_e32 v13, 0xffff0000, v8
	v_lshlrev_b32_e32 v8, 16, v9
	v_and_b32_e32 v9, 0xffff0000, v9
	s_waitcnt lgkmcnt(1)
	v_pk_fma_f32 v[2:3], s[6:7], v[2:3], v[8:9]
	v_add_co_u32_e32 v8, vcc, s90, v130
	v_lshlrev_b32_e32 v14, 16, v10
	v_and_b32_e32 v15, 0xffff0000, v10
	v_lshlrev_b32_e32 v10, 16, v11
	v_and_b32_e32 v11, 0xffff0000, v11
	v_pk_fma_f32 v[0:1], s[40:41], v[0:1], v[12:13] neg_lo:[1,0,0] neg_hi:[1,0,0]
	v_addc_co_u32_e32 v9, vcc, 0, v131, vcc
	global_store_dwordx4 v[8:9], v[0:3], off offset:512
	s_waitcnt lgkmcnt(0)
	s_nop 0
	v_pk_fma_f32 v[2:3], s[6:7], v[6:7], v[10:11]
	v_pk_fma_f32 v[0:1], s[40:41], v[4:5], v[14:15] neg_lo:[1,0,0] neg_hi:[1,0,0]
	global_store_dwordx4 v[8:9], v[0:3], off offset:528
	v_add_co_u32_e32 v8, vcc, s67, v128
	ds_read_b128 v[0:3], v132 offset:8192
	ds_read_b128 v[4:7], v132 offset:8208
	v_addc_co_u32_e32 v9, vcc, 0, v129, vcc
	v_mov_b32_e32 v8, v112
	v_mov_b32_e32 v9, v113
	v_mov_b32_e32 v10, v114
	v_mov_b32_e32 v11, v115
	v_lshlrev_b32_e32 v12, 16, v8
	v_and_b32_e32 v13, 0xffff0000, v8
	v_lshlrev_b32_e32 v8, 16, v9
	v_and_b32_e32 v9, 0xffff0000, v9
	s_waitcnt lgkmcnt(1)
; __device__ __forceinline__ float bf_lo(unsigned v) { return __uint_as_float(v << 16); }
; __device__ __forceinline__ float bf_hi(unsigned v) { return __uint_as_float(v & 0xffff0000u); }
; __device__ __forceinline__ void attn_pass(const bf16_t* __restrict__ Qb, const bf16_t* __restrict__ Kh, const bf16_t* __restrict__ Vh,
;                                           float* Ob, int mode, float lam, int qpos0, int seq, char* lds, const int wv, bf16_t* OBh) {
;     ...
;       for (int k = 0; k < 8; ++k) { const f32x4 v0 = *(const f32x4*)(sl + k * 512), v1 = *(const f32x4*)(sl + k * 512 + 4);
;         const u32x4 pw = *(const u32x4*)(OBw + (long)(4 * k) * DM + half * 128);
;         const f32x4 p0 = {bf_lo(pw.x), bf_hi(pw.x), bf_lo(pw.y), bf_hi(pw.y)}, p1 = {bf_lo(pw.z), bf_hi(pw.z), bf_lo(pw.w), bf_hi(pw.w)};
;         float* gp = Ow + (long)(4 * k) * LDO + half * 128;
;         *(f32x4*)gp = p0 - lam * v0; *(f32x4*)(gp + 4) = p1 - lam * v1; }
	v_pk_fma_f32 v[2:3], s[6:7], v[2:3], v[8:9]
	v_add_co_u32_e32 v8, vcc, s50, v130
	v_lshlrev_b32_e32 v14, 16, v10
	v_and_b32_e32 v15, 0xffff0000, v10
	v_lshlrev_b32_e32 v10, 16, v11
	v_and_b32_e32 v11, 0xffff0000, v11
	v_pk_fma_f32 v[0:1], s[40:41], v[0:1], v[12:13] neg_lo:[1,0,0] neg_hi:[1,0,0]
	v_addc_co_u32_e32 v9, vcc, 0, v131, vcc
	global_store_dwordx4 v[8:9], v[0:3], off offset:512
	s_waitcnt lgkmcnt(0)
	s_nop 0
	v_pk_fma_f32 v[2:3], s[6:7], v[6:7], v[10:11]
	v_pk_fma_f32 v[0:1], s[40:41], v[4:5], v[14:15] neg_lo:[1,0,0] neg_hi:[1,0,0]
	global_store_dwordx4 v[8:9], v[0:3], off offset:528
	v_add_co_u32_e32 v8, vcc, s75, v128
	ds_read_b128 v[0:3], v132 offset:10240
	ds_read_b128 v[4:7], v132 offset:10256
	v_addc_co_u32_e32 v9, vcc, 0, v129, vcc
	v_mov_b32_e32 v8, v116
	v_mov_b32_e32 v9, v117
	v_mov_b32_e32 v10, v118
	v_mov_b32_e32 v11, v119
	v_lshlrev_b32_e32 v12, 16, v8
	v_and_b32_e32 v13, 0xffff0000, v8
	v_lshlrev_b32_e32 v8, 16, v9
	v_and_b32_e32 v9, 0xffff0000, v9
	s_waitcnt lgkmcnt(1)
	v_pk_fma_f32 v[2:3], s[6:7], v[2:3], v[8:9]
	v_add_co_u32_e32 v8, vcc, s51, v130
	v_lshlrev_b32_e32 v14, 16, v10
	v_and_b32_e32 v15, 0xffff0000, v10
	v_lshlrev_b32_e32 v10, 16, v11
	v_and_b32_e32 v11, 0xffff0000, v11
	v_pk_fma_f32 v[0:1], s[40:41], v[0:1], v[12:13] neg_lo:[1,0,0] neg_hi:[1,0,0]
	v_addc_co_u32_e32 v9, vcc, 0, v131, vcc
	global_store_dwordx4 v[8:9], v[0:3], off offset:512
	s_waitcnt lgkmcnt(0)
	s_nop 0
	v_pk_fma_f32 v[2:3], s[6:7], v[6:7], v[10:11]
	v_pk_fma_f32 v[0:1], s[40:41], v[4:5], v[14:15] neg_lo:[1,0,0] neg_hi:[1,0,0]
	global_store_dwordx4 v[8:9], v[0:3], off offset:528
	v_add_co_u32_e32 v8, vcc, s90, v128
	ds_read_b128 v[0:3], v132 offset:12288
	ds_read_b128 v[4:7], v132 offset:12304
	v_addc_co_u32_e32 v9, vcc, 0, v129, vcc
	v_mov_b32_e32 v8, v120
	v_mov_b32_e32 v9, v121
	v_mov_b32_e32 v10, v122
	v_mov_b32_e32 v11, v123
	v_lshlrev_b32_e32 v12, 16, v8
	v_and_b32_e32 v13, 0xffff0000, v8
	v_lshlrev_b32_e32 v8, 16, v9
	v_and_b32_e32 v9, 0xffff0000, v9
	s_waitcnt lgkmcnt(1)
	v_pk_fma_f32 v[2:3], s[6:7], v[2:3], v[8:9]
	v_add_co_u32_e32 v8, vcc, s78, v130
	v_lshlrev_b32_e32 v14, 16, v10
	v_and_b32_e32 v15, 0xffff0000, v10
	v_lshlrev_b32_e32 v10, 16, v11
	v_and_b32_e32 v11, 0xffff0000, v11
	v_pk_fma_f32 v[0:1], s[40:41], v[0:1], v[12:13] neg_lo:[1,0,0] neg_hi:[1,0,0]
	v_addc_co_u32_e32 v9, vcc, 0, v131, vcc
	global_store_dwordx4 v[8:9], v[0:3], off offset:512
	s_waitcnt lgkmcnt(0)
	s_nop 0
	v_pk_fma_f32 v[2:3], s[6:7], v[6:7], v[10:11]
	v_pk_fma_f32 v[0:1], s[40:41], v[4:5], v[14:15] neg_lo:[1,0,0] neg_hi:[1,0,0]
	global_store_dwordx4 v[8:9], v[0:3], off offset:528
	v_add_co_u32_e32 v8, vcc, s33, v128
	ds_read_b128 v[0:3], v132 offset:14336
	ds_read_b128 v[4:7], v132 offset:14352
	v_addc_co_u32_e32 v9, vcc, 0, v129, vcc
	v_mov_b32_e32 v8, v124
	v_mov_b32_e32 v9, v125
	v_mov_b32_e32 v10, v126
	v_mov_b32_e32 v11, v127
	v_lshlrev_b32_e32 v12, 16, v8
	v_and_b32_e32 v13, 0xffff0000, v8
	v_lshlrev_b32_e32 v8, 16, v9
	v_and_b32_e32 v9, 0xffff0000, v9
	s_waitcnt lgkmcnt(1)
	v_pk_fma_f32 v[2:3], s[6:7], v[2:3], v[8:9]
	v_add_co_u32_e32 v8, vcc, 0x38000, v130
	v_lshlrev_b32_e32 v14, 16, v10
	v_and_b32_e32 v15, 0xffff0000, v10
	v_lshlrev_b32_e32 v10, 16, v11
	v_and_b32_e32 v11, 0xffff0000, v11
	v_pk_fma_f32 v[0:1], s[40:41], v[0:1], v[12:13] neg_lo:[1,0,0] neg_hi:[1,0,0]
	v_addc_co_u32_e32 v9, vcc, 0, v131, vcc
	global_store_dwordx4 v[8:9], v[0:3], off offset:512
	s_waitcnt lgkmcnt(0)
	s_nop 0
	v_pk_fma_f32 v[2:3], s[6:7], v[6:7], v[10:11]
	v_pk_fma_f32 v[0:1], s[40:41], v[4:5], v[14:15] neg_lo:[1,0,0] neg_hi:[1,0,0]
	s_mov_b64 s[6:7], 0
	global_store_dwordx4 v[8:9], v[0:3], off offset:528

; #define LAS __attribute__((address_space(3)))
; __device__ __forceinline__ int otid(int wv) { int l; asm volatile("v_mbcnt_lo_u32_b32 %0, -1, 0\n\tv_mbcnt_hi_u32_b32 %0, -1, %0" : "=v"(l)); return wv * 64 + l; }
; __device__ __forceinline__ void conv_item(int it, const bf16_t* AG, const float* dw, const float* cg_, const float* cb_, bf16_t* CAT, unsigned char* lds, const int wv) {
;     const int tid = otid(wv), wid = __builtin_amdgcn_readfirstlane(tid >> 6), lane = tid & 63;
;     const int t0 = it * 32, b = t0 >> 12, s0 = t0 & 4095;
;     LAS unsigned char* X = (LAS unsigned char*)lds;
;     LAS f32x2* red = (LAS f32x2*)(X + 62 * 2048);
;     LAS f32x2* stat = red + 256;
;     __syncthreads();
; #pragma unroll
;     for (int p = 0; p < 16; ++p) { const int r = p * 4 + (tid >> 7);
;         if (r < 62) { const int sp = s0 - 15 + r; u32x4 val = {0u, 0u, 0u, 0u};
;             if (sp >= 0 && sp < SEQ) val = *(const u32x4*)(AG + ((size_t)(b * SEQ + sp)) * 1024 + 8 * (tid & 127));
;             *(LAS u32x4*)(X + r * 2048 + 16 * (tid & 127)) = val; } }
.LBB0_156:
	v_mbcnt_lo_u32_b32 v128, -1, 0
	v_mbcnt_hi_u32_b32 v128, -1, v128
	v_readlane_b32 s4, v255, 17
	v_add_u32_e32 v190, s3, v128
	v_lshlrev_b32_e32 v0, 4, v190
	s_and_b32 s17, s12, 0xfe0
	v_ashrrev_i32_e32 v192, 7, v190
	v_and_b32_e32 v210, 0x7f0, v0
	v_readlane_b32 s5, v255, 18
	v_readfirstlane_b32 s1, v190
	s_add_i32 s17, s17, -15
	s_and_b32 s2, s12, 0xfffff000
	v_lshl_add_u64 v[4:5], s[4:5], 0, v[210:211]
	v_add_u32_e32 v191, 0, v210
	v_cmp_gt_i32_e32 vcc, 62, v192
	s_waitcnt vmcnt(0)
	s_barrier
	s_mov_b64 s[4:5], exec
	v_mov_b32_e32 v6, v192
	v_add_u32_e32 v7, s17, v6
	v_mov_b32_e32 v64, 0
	v_mov_b32_e32 v65, 0
	v_mov_b32_e32 v66, 0
	v_mov_b32_e32 v67, 0
	v_cmp_gt_u32_e32 vcc, s22, v7
	s_and_saveexec_b64 s[10:11], vcc
	v_or_b32_e32 v0, s2, v7
	v_ashrrev_i32_e32 v1, 31, v0
	v_lshlrev_b64 v[0:1], 11, v[0:1]
	v_lshl_add_u64 v[0:1], v[4:5], 0, v[0:1]
	global_load_dwordx4 v[64:67], v[0:1], off
	s_mov_b64 exec, s[10:11]
	v_add_u32_e32 v6, 4, v192
	v_add_u32_e32 v7, s17, v6
	v_mov_b32_e32 v68, 0
	v_mov_b32_e32 v69, 0
	v_mov_b32_e32 v70, 0
	v_mov_b32_e32 v71, 0
	v_cmp_gt_u32_e32 vcc, s22, v7
	s_and_saveexec_b64 s[10:11], vcc
	v_or_b32_e32 v0, s2, v7
	v_ashrrev_i32_e32 v1, 31, v0
	v_lshlrev_b64 v[0:1], 11, v[0:1]
	v_lshl_add_u64 v[0:1], v[4:5], 0, v[0:1]
	global_load_dwordx4 v[68:71], v[0:1], off
	s_mov_b64 exec, s[10:11]
	v_add_u32_e32 v6, 8, v192
	v_add_u32_e32 v7, s17, v6
	v_mov_b32_e32 v72, 0
	v_mov_b32_e32 v73, 0
	v_mov_b32_e32 v74, 0
	v_mov_b32_e32 v75, 0
	v_cmp_gt_u32_e32 vcc, s22, v7
	s_and_saveexec_b64 s[10:11], vcc
	v_or_b32_e32 v0, s2, v7
	v_ashrrev_i32_e32 v1, 31, v0
	v_lshlrev_b64 v[0:1], 11, v[0:1]
	v_lshl_add_u64 v[0:1], v[4:5], 0, v[0:1]
	global_load_dwordx4 v[72:75], v[0:1], off
	s_mov_b64 exec, s[10:11]
	v_add_u32_e32 v6, 12, v192
	v_add_u32_e32 v7, s17, v6
	v_mov_b32_e32 v76, 0
	v_mov_b32_e32 v77, 0
	v_mov_b32_e32 v78, 0
	v_mov_b32_e32 v79, 0
	v_cmp_gt_u32_e32 vcc, s22, v7
	s_and_saveexec_b64 s[10:11], vcc
	v_or_b32_e32 v0, s2, v7
	v_ashrrev_i32_e32 v1, 31, v0
	v_lshlrev_b64 v[0:1], 11, v[0:1]
	v_lshl_add_u64 v[0:1], v[4:5], 0, v[0:1]
	global_load_dwordx4 v[76:79], v[0:1], off
	s_mov_b64 exec, s[10:11]
	v_add_u32_e32 v6, 16, v192
	v_add_u32_e32 v7, s17, v6
	v_mov_b32_e32 v80, 0
	v_mov_b32_e32 v81, 0
	v_mov_b32_e32 v82, 0
	v_mov_b32_e32 v83, 0
	v_cmp_gt_u32_e32 vcc, s22, v7
	s_and_saveexec_b64 s[10:11], vcc
	v_or_b32_e32 v0, s2, v7
	v_ashrrev_i32_e32 v1, 31, v0
	v_lshlrev_b64 v[0:1], 11, v[0:1]
	v_lshl_add_u64 v[0:1], v[4:5], 0, v[0:1]
	global_load_dwordx4 v[80:83], v[0:1], off
	s_mov_b64 exec, s[10:11]
	v_add_u32_e32 v6, 20, v192
	v_add_u32_e32 v7, s17, v6
	v_mov_b32_e32 v84, 0
	v_mov_b32_e32 v85, 0
	v_mov_b32_e32 v86, 0
	v_mov_b32_e32 v87, 0
	v_cmp_gt_u32_e32 vcc, s22, v7
	s_and_saveexec_b64 s[10:11], vcc
	v_or_b32_e32 v0, s2, v7
	v_ashrrev_i32_e32 v1, 31, v0
	v_lshlrev_b64 v[0:1], 11, v[0:1]
	v_lshl_add_u64 v[0:1], v[4:5], 0, v[0:1]
	global_load_dwordx4 v[84:87], v[0:1], off
	s_mov_b64 exec, s[10:11]
	v_add_u32_e32 v6, 24, v192
	v_add_u32_e32 v7, s17, v6
	v_mov_b32_e32 v88, 0
	v_mov_b32_e32 v89, 0
	v_mov_b32_e32 v90, 0
	v_mov_b32_e32 v91, 0
	v_cmp_gt_u32_e32 vcc, s22, v7
	s_and_saveexec_b64 s[10:11], vcc
	v_or_b32_e32 v0, s2, v7
	v_ashrrev_i32_e32 v1, 31, v0
	v_lshlrev_b64 v[0:1], 11, v[0:1]
	v_lshl_add_u64 v[0:1], v[4:5], 0, v[0:1]
	global_load_dwordx4 v[88:91], v[0:1], off
	s_mov_b64 exec, s[10:11]
	v_add_u32_e32 v6, 28, v192
	v_add_u32_e32 v7, s17, v6
	v_mov_b32_e32 v92, 0
	v_mov_b32_e32 v93, 0
	v_mov_b32_e32 v94, 0
	v_mov_b32_e32 v95, 0
	v_cmp_gt_u32_e32 vcc, s22, v7
	s_and_saveexec_b64 s[10:11], vcc
	v_or_b32_e32 v0, s2, v7
	v_ashrrev_i32_e32 v1, 31, v0
	v_lshlrev_b64 v[0:1], 11, v[0:1]
	v_lshl_add_u64 v[0:1], v[4:5], 0, v[0:1]
	global_load_dwordx4 v[92:95], v[0:1], off
	s_mov_b64 exec, s[10:11]
	v_add_u32_e32 v6, 32, v192
	v_add_u32_e32 v7, s17, v6
	v_mov_b32_e32 v96, 0
	v_mov_b32_e32 v97, 0
	v_mov_b32_e32 v98, 0
	v_mov_b32_e32 v99, 0
	v_cmp_gt_u32_e32 vcc, s22, v7
	s_and_saveexec_b64 s[10:11], vcc
	v_or_b32_e32 v0, s2, v7
	v_ashrrev_i32_e32 v1, 31, v0
	v_lshlrev_b64 v[0:1], 11, v[0:1]
	v_lshl_add_u64 v[0:1], v[4:5], 0, v[0:1]
	global_load_dwordx4 v[96:99], v[0:1], off
	s_mov_b64 exec, s[10:11]
	v_add_u32_e32 v6, 36, v192
	v_add_u32_e32 v7, s17, v6
	v_mov_b32_e32 v100, 0
	v_mov_b32_e32 v101, 0
	v_mov_b32_e32 v102, 0
	v_mov_b32_e32 v103, 0
; #define LAS __attribute__((address_space(3)))
; __device__ __forceinline__ void conv_item(int it, const bf16_t* AG, const float* dw, const float* cg_, const float* cb_, bf16_t* CAT, unsigned char* lds, const int wv) {
;     ...
;     for (int p = 0; p < 16; ++p) { const int r = p * 4 + (tid >> 7);
;         if (r < 62) { const int sp = s0 - 15 + r; u32x4 val = {0u, 0u, 0u, 0u};
;             if (sp >= 0 && sp < SEQ) val = *(const u32x4*)(AG + ((size_t)(b * SEQ + sp)) * 1024 + 8 * (tid & 127));
;             *(LAS u32x4*)(X + r * 2048 + 16 * (tid & 127)) = val; } }
	v_cmp_gt_u32_e32 vcc, s22, v7
	s_and_saveexec_b64 s[10:11], vcc
	v_or_b32_e32 v0, s2, v7
	v_ashrrev_i32_e32 v1, 31, v0
	v_lshlrev_b64 v[0:1], 11, v[0:1]
	v_lshl_add_u64 v[0:1], v[4:5], 0, v[0:1]
	global_load_dwordx4 v[100:103], v[0:1], off
	s_mov_b64 exec, s[10:11]
	v_add_u32_e32 v6, 40, v192
	v_add_u32_e32 v7, s17, v6
	v_mov_b32_e32 v104, 0
	v_mov_b32_e32 v105, 0
	v_mov_b32_e32 v106, 0
	v_mov_b32_e32 v107, 0
	v_cmp_gt_u32_e32 vcc, s22, v7
	s_and_saveexec_b64 s[10:11], vcc
	v_or_b32_e32 v0, s2, v7
	v_ashrrev_i32_e32 v1, 31, v0
	v_lshlrev_b64 v[0:1], 11, v[0:1]
	v_lshl_add_u64 v[0:1], v[4:5], 0, v[0:1]
	global_load_dwordx4 v[104:107], v[0:1], off
	s_mov_b64 exec, s[10:11]
	v_add_u32_e32 v6, 44, v192
	v_add_u32_e32 v7, s17, v6
	v_mov_b32_e32 v108, 0
	v_mov_b32_e32 v109, 0
	v_mov_b32_e32 v110, 0
	v_mov_b32_e32 v111, 0
	v_cmp_gt_u32_e32 vcc, s22, v7
	s_and_saveexec_b64 s[10:11], vcc
	v_or_b32_e32 v0, s2, v7
	v_ashrrev_i32_e32 v1, 31, v0
	v_lshlrev_b64 v[0:1], 11, v[0:1]
	v_lshl_add_u64 v[0:1], v[4:5], 0, v[0:1]
	global_load_dwordx4 v[108:111], v[0:1], off
	s_mov_b64 exec, s[10:11]
	v_add_u32_e32 v6, 48, v192
	v_add_u32_e32 v7, s17, v6
	v_mov_b32_e32 v112, 0
	v_mov_b32_e32 v113, 0
	v_mov_b32_e32 v114, 0
	v_mov_b32_e32 v115, 0
	v_cmp_gt_u32_e32 vcc, s22, v7
	s_and_saveexec_b64 s[10:11], vcc
	v_or_b32_e32 v0, s2, v7
	v_ashrrev_i32_e32 v1, 31, v0
	v_lshlrev_b64 v[0:1], 11, v[0:1]
	v_lshl_add_u64 v[0:1], v[4:5], 0, v[0:1]
	global_load_dwordx4 v[112:115], v[0:1], off
	s_mov_b64 exec, s[10:11]
	v_add_u32_e32 v6, 52, v192
	v_add_u32_e32 v7, s17, v6
	v_mov_b32_e32 v116, 0
	v_mov_b32_e32 v117, 0
	v_mov_b32_e32 v118, 0
	v_mov_b32_e32 v119, 0
	v_cmp_gt_u32_e32 vcc, s22, v7
	s_and_saveexec_b64 s[10:11], vcc
	v_or_b32_e32 v0, s2, v7
	v_ashrrev_i32_e32 v1, 31, v0
	v_lshlrev_b64 v[0:1], 11, v[0:1]
	v_lshl_add_u64 v[0:1], v[4:5], 0, v[0:1]
	global_load_dwordx4 v[116:119], v[0:1], off
	s_mov_b64 exec, s[10:11]
	v_add_u32_e32 v6, 56, v192
	v_add_u32_e32 v7, s17, v6
	v_mov_b32_e32 v120, 0
	v_mov_b32_e32 v121, 0
	v_mov_b32_e32 v122, 0
	v_mov_b32_e32 v123, 0
	v_cmp_gt_u32_e32 vcc, s22, v7
	s_and_saveexec_b64 s[10:11], vcc
	v_or_b32_e32 v0, s2, v7
	v_ashrrev_i32_e32 v1, 31, v0
	v_lshlrev_b64 v[0:1], 11, v[0:1]
	v_lshl_add_u64 v[0:1], v[4:5], 0, v[0:1]
	global_load_dwordx4 v[120:123], v[0:1], off
	s_mov_b64 exec, s[10:11]
	v_add_u32_e32 v6, 60, v192
	v_add_u32_e32 v7, s17, v6
	v_mov_b32_e32 v124, 0
	v_mov_b32_e32 v125, 0
	v_mov_b32_e32 v126, 0
	v_mov_b32_e32 v127, 0
	v_cmp_gt_u32_e32 vcc, s22, v7
	v_cmp_gt_i32_e64 s[10:11], 62, v6
	s_and_b64 vcc, vcc, s[10:11]
	s_and_saveexec_b64 s[10:11], vcc
	v_or_b32_e32 v0, s2, v7
	v_ashrrev_i32_e32 v1, 31, v0
	v_lshlrev_b64 v[0:1], 11, v[0:1]
	v_lshl_add_u64 v[0:1], v[4:5], 0, v[0:1]
	global_load_dwordx4 v[124:127], v[0:1], off
	s_mov_b64 exec, s[10:11]
	s_waitcnt vmcnt(0)
	v_lshl_add_u32 v6, v192, 11, v191
	ds_write_b128 v6, v[64:67]
	v_add_u32_e32 v7, 4, v192
	v_lshl_add_u32 v6, v7, 11, v191
	ds_write_b128 v6, v[68:71]
	v_add_u32_e32 v7, 8, v192
	v_lshl_add_u32 v6, v7, 11, v191
	ds_write_b128 v6, v[72:75]
	v_add_u32_e32 v7, 12, v192
	v_lshl_add_u32 v6, v7, 11, v191
	ds_write_b128 v6, v[76:79]
	v_add_u32_e32 v7, 16, v192
	v_lshl_add_u32 v6, v7, 11, v191
	ds_write_b128 v6, v[80:83]
	v_add_u32_e32 v7, 20, v192
	v_lshl_add_u32 v6, v7, 11, v191
	ds_write_b128 v6, v[84:87]
	v_add_u32_e32 v7, 24, v192
	v_lshl_add_u32 v6, v7, 11, v191
	ds_write_b128 v6, v[88:91]
	v_add_u32_e32 v7, 28, v192
	v_lshl_add_u32 v6, v7, 11, v191
	ds_write_b128 v6, v[92:95]
	v_add_u32_e32 v7, 32, v192
	v_lshl_add_u32 v6, v7, 11, v191
	ds_write_b128 v6, v[96:99]
	v_add_u32_e32 v7, 36, v192
	v_lshl_add_u32 v6, v7, 11, v191
	ds_write_b128 v6, v[100:103]
	v_add_u32_e32 v7, 40, v192
	v_lshl_add_u32 v6, v7, 11, v191
	ds_write_b128 v6, v[104:107]
	v_add_u32_e32 v7, 44, v192
	v_lshl_add_u32 v6, v7, 11, v191
	ds_write_b128 v6, v[108:111]
	v_add_u32_e32 v7, 48, v192
	v_lshl_add_u32 v6, v7, 11, v191
	ds_write_b128 v6, v[112:115]
	v_add_u32_e32 v7, 52, v192
	v_lshl_add_u32 v6, v7, 11, v191
	ds_write_b128 v6, v[116:119]
	v_add_u32_e32 v7, 56, v192
	v_lshl_add_u32 v6, v7, 11, v191
	ds_write_b128 v6, v[120:123]
	v_add_u32_e32 v7, 60, v192
	v_lshl_add_u32 v6, v7, 11, v191
	v_cmp_gt_i32_e32 vcc, 62, v7
	s_and_saveexec_b64 s[10:11], vcc
	ds_write_b128 v6, v[124:127]
	s_mov_b64 exec, s[10:11]
